# GU GEMM k-loop rewritten with v_mfma_f32_16x16x32_bf16 (f32 acc), swizzled unpadded B LDS tile, permlane16/32_swap re-layout before the existing epilogue
# speedup vs baseline: 1.0074x; 1.0074x over previous
.LBB0_1031:
	s_mul_hi_i32 s0, s2, 0x2e8ba2e9
	s_lshr_b32 s1, s0, 31
	s_ashr_i32 s0, s0, 6
	s_add_i32 s0, s0, s1
	s_lshl_b32 s1, s0, 3
	s_sub_i32 s7, s25, s1
	s_min_i32 s7, s7, 8
	s_abs_i32 s8, s7
	v_cvt_f32_u32_e32 v0, s8
	s_sub_i32 s11, 0, s8
	s_mulk_i32 s0, 0xfea0
	s_add_i32 s9, s0, s2
	v_rcp_iflag_f32_e32 v0, v0
	s_abs_i32 s0, s9
	s_xor_b32 s10, s9, s7
	s_ashr_i32 s10, s10, 31
	v_mul_f32_e32 v0, 0x4f7ffffe, v0
	v_cvt_u32_f32_e32 v0, v0
	v_mov_b32_e32 v237, v179
	v_readfirstlane_b32 s12, v0
	s_mul_i32 s11, s11, s12
	s_mul_hi_u32 s11, s12, s11
	s_add_i32 s12, s12, s11
	s_mul_hi_u32 s11, s0, s12
	s_mul_i32 s12, s11, s8
	s_sub_i32 s0, s0, s12
	s_add_i32 s13, s11, 1
	s_sub_i32 s12, s0, s8
	s_cmp_ge_u32 s0, s8
	s_cselect_b32 s11, s13, s11
	s_cselect_b32 s0, s12, s0
	s_add_i32 s12, s11, 1
	s_cmp_ge_u32 s0, s8
	s_cselect_b32 s0, s12, s11
	s_xor_b32 s0, s0, s10
	s_sub_i32 s0, s0, s10
	s_mul_i32 s7, s7, s0
	s_sub_i32 s7, s9, s7
	s_add_i32 s1, s1, s6
	v_ashrrev_i32_e32 v238, 6, v237
	s_add_i32 s7, s1, s7
	v_lshlrev_b32_e32 v0, 1, v238
	v_lshl_add_u32 v0, s7, 3, v0
	v_ashrrev_i32_e32 v1, 31, v0
	v_bfe_u32 v183, v237, 5, 1
	v_lshlrev_b64 v[0:1], 16, v[0:1]
	v_and_b32_e32 v239, 31, v237
	v_lshl_add_u64 v[0:1], s[64:65], 0, v[0:1]
	v_lshlrev_b32_e32 v176, 9, v183
	s_ashr_i32 s1, s0, 31
	v_lshl_add_u64 v[0:1], v[0:1], 0, v[176:177]
	v_lshlrev_b32_e32 v176, 4, v239
	v_ashrrev_i32_e32 v38, 2, v237
	s_lshl_b64 s[8:9], s[0:1], 18
	v_lshl_add_u64 v[184:185], v[0:1], 0, v[176:177]
	s_add_u32 s8, s4, s8
	v_lshlrev_b32_e32 v0, 5, v38
	v_lshlrev_b32_e32 v2, 3, v237
	s_addc_u32 s9, s5, s9
	v_ashrrev_i32_e32 v1, 31, v0
	v_and_b32_e32 v181, 24, v2
	v_lshl_add_u64 v[0:1], v[0:1], 1, s[8:9]
	v_lshlrev_b32_e32 v176, 1, v181
	v_lshl_add_u64 v[186:187], v[0:1], 0, v[176:177]
	s_movk_i32 s1, 0x2000
	v_add_co_u32_e32 v34, vcc, s1, v186
	v_mul_u32_u24_e32 v36, 40, v239
	s_nop 0
	v_addc_co_u32_e32 v35, vcc, 0, v187, vcc
	v_lshlrev_b32_e32 v37, 4, v183
	v_lshl_add_u32 v241, v36, 1, v37
	v_add_co_u32_e32 v36, vcc, s41, v184
	s_movk_i32 s8, 0x50
	s_nop 0
	v_addc_co_u32_e32 v37, vcc, 0, v185, vcc
	v_mad_u64_u32 v[188:189], s[8:9], v38, s8, v[176:177]
	v_and_b32_e32 v240, 63, v237
	v_mov_b32_e32 v176, 0x800
	v_lshl_add_u64 v[188:189], v[186:187], 0, v[176:177]
	v_bfe_u32 v247, v237, 4, 1
	v_lshlrev_b32_e32 v176, 9, v183
	v_lshl_add_u32 v176, v247, 8, v176
	v_lshl_add_u64 v[184:185], v[184:185], 0, v[176:177]
	v_mov_b32_e32 v176, s41
	v_lshl_add_u64 v[186:187], v[184:185], 0, v[176:177]
	v_lshrrev_b32_e32 v241, 2, v237
	v_bfe_u32 v247, v237, 4, 2
	v_lshlrev_b32_e32 v247, 1, v247
	v_mov_b32_e32 v176, 0x78
	v_lshrrev_b32_e32 v247, v247, v176
	v_and_b32_e32 v247, 3, v247
	v_and_b32_e32 v246, 3, v237
	v_xor_b32_e32 v247, v247, v246
	v_lshlrev_b32_e32 v247, 4, v247
	v_lshl_add_u32 v241, v241, 6, v247
	v_bfe_u32 v247, v237, 2, 2
	v_lshlrev_b32_e32 v247, 1, v247
	v_lshrrev_b32_e32 v247, v247, v176
	v_and_b32_e32 v247, 3, v247
	v_bfe_u32 v246, v237, 4, 2
	v_xor_b32_e32 v247, v247, v246
	v_lshlrev_b32_e32 v247, 4, v247
	v_and_b32_e32 v246, 15, v237
	v_lshl_add_u32 v246, v246, 6, v247
	s_mov_b32 s96, 0
	v_lshl_add_u64 v[166:167], v[188:189], 0, s[96:97]
	global_load_dwordx4 v[160:163], v[166:167], off offset:-2048
	global_load_dwordx4 v[164:167], v[166:167], off offset:2048
	v_lshl_add_u64 v[248:249], v[184:185], 0, s[96:97]
	v_lshl_add_u64 v[250:251], v[186:187], 0, s[96:97]
	global_load_dwordx4 v[128:131], v[248:249], off
	global_load_dwordx4 v[132:135], v[248:249], off offset:256
	global_load_dwordx4 v[136:139], v[250:251], off
	global_load_dwordx4 v[140:143], v[250:251], off offset:256
	s_movk_i32 s96, 0x2000
	v_lshl_add_u64 v[174:175], v[188:189], 0, s[96:97]
	global_load_dwordx4 v[168:171], v[174:175], off offset:-2048
	global_load_dwordx4 v[172:175], v[174:175], off offset:2048
	s_movk_i32 s96, 0x800
	v_lshl_add_u64 v[248:249], v[184:185], 0, s[96:97]
	v_lshl_add_u64 v[250:251], v[186:187], 0, s[96:97]
	global_load_dwordx4 v[144:147], v[248:249], off
	global_load_dwordx4 v[148:151], v[248:249], off offset:256
	global_load_dwordx4 v[152:155], v[250:251], off
	global_load_dwordx4 v[156:159], v[250:251], off offset:256
	v_mov_b32_e32 v0, 0
	v_mov_b32_e32 v1, 0
	v_mov_b32_e32 v2, 0
	v_mov_b32_e32 v3, 0
	v_mov_b32_e32 v4, 0
	v_mov_b32_e32 v5, 0
	v_mov_b32_e32 v6, 0
	v_mov_b32_e32 v7, 0
	v_mov_b32_e32 v8, 0
	v_mov_b32_e32 v9, 0
	v_mov_b32_e32 v10, 0
	v_mov_b32_e32 v11, 0
	v_mov_b32_e32 v12, 0
	v_mov_b32_e32 v13, 0
	v_mov_b32_e32 v14, 0
	v_mov_b32_e32 v15, 0
	v_mov_b32_e32 v16, 0
	v_mov_b32_e32 v17, 0
	v_mov_b32_e32 v18, 0
	v_mov_b32_e32 v19, 0
	v_mov_b32_e32 v20, 0
	v_mov_b32_e32 v21, 0
	v_mov_b32_e32 v22, 0
	v_mov_b32_e32 v23, 0
	v_mov_b32_e32 v24, 0
	v_mov_b32_e32 v25, 0
	v_mov_b32_e32 v26, 0
	v_mov_b32_e32 v27, 0
	v_mov_b32_e32 v28, 0
	v_mov_b32_e32 v29, 0
	v_mov_b32_e32 v30, 0
	v_mov_b32_e32 v31, 0
	v_mov_b32_e32 v32, 0
	v_mov_b32_e32 v33, 0
	v_mov_b32_e32 v34, 0
	v_mov_b32_e32 v35, 0
	v_mov_b32_e32 v36, 0
	v_mov_b32_e32 v37, 0
	v_mov_b32_e32 v38, 0
	v_mov_b32_e32 v39, 0
	v_mov_b32_e32 v40, 0
	v_mov_b32_e32 v41, 0
	v_mov_b32_e32 v42, 0
	v_mov_b32_e32 v43, 0
	v_mov_b32_e32 v44, 0
	v_mov_b32_e32 v45, 0
	v_mov_b32_e32 v46, 0
	v_mov_b32_e32 v47, 0
	v_mov_b32_e32 v48, 0
	v_mov_b32_e32 v49, 0
	v_mov_b32_e32 v50, 0
	v_mov_b32_e32 v51, 0
	v_mov_b32_e32 v52, 0
	v_mov_b32_e32 v53, 0
	v_mov_b32_e32 v54, 0
	v_mov_b32_e32 v55, 0
	v_mov_b32_e32 v56, 0
	v_mov_b32_e32 v57, 0
	v_mov_b32_e32 v58, 0
	v_mov_b32_e32 v59, 0
	v_mov_b32_e32 v60, 0
	v_mov_b32_e32 v61, 0
	v_mov_b32_e32 v62, 0
	v_mov_b32_e32 v63, 0
	v_mov_b32_e32 v64, 0
	v_mov_b32_e32 v65, 0
	v_mov_b32_e32 v66, 0
	v_mov_b32_e32 v67, 0
	v_mov_b32_e32 v68, 0
	v_mov_b32_e32 v69, 0
	v_mov_b32_e32 v70, 0
	v_mov_b32_e32 v71, 0
	v_mov_b32_e32 v72, 0
	v_mov_b32_e32 v73, 0
	v_mov_b32_e32 v74, 0
	v_mov_b32_e32 v75, 0
	v_mov_b32_e32 v76, 0
	v_mov_b32_e32 v77, 0
	v_mov_b32_e32 v78, 0
	v_mov_b32_e32 v79, 0
	v_mov_b32_e32 v80, 0
	v_mov_b32_e32 v81, 0
	v_mov_b32_e32 v82, 0
	v_mov_b32_e32 v83, 0
	v_mov_b32_e32 v84, 0
	v_mov_b32_e32 v85, 0
	v_mov_b32_e32 v86, 0
	v_mov_b32_e32 v87, 0
	v_mov_b32_e32 v88, 0
	v_mov_b32_e32 v89, 0
	v_mov_b32_e32 v90, 0
	v_mov_b32_e32 v91, 0
	v_mov_b32_e32 v92, 0
	v_mov_b32_e32 v93, 0
	v_mov_b32_e32 v94, 0
	v_mov_b32_e32 v95, 0
	v_mov_b32_e32 v96, 0
	v_mov_b32_e32 v97, 0
	v_mov_b32_e32 v98, 0
	v_mov_b32_e32 v99, 0
	v_mov_b32_e32 v100, 0
	v_mov_b32_e32 v101, 0
	v_mov_b32_e32 v102, 0
	v_mov_b32_e32 v103, 0
	v_mov_b32_e32 v104, 0
	v_mov_b32_e32 v105, 0
	v_mov_b32_e32 v106, 0
	v_mov_b32_e32 v107, 0
	v_mov_b32_e32 v108, 0
	v_mov_b32_e32 v109, 0
	v_mov_b32_e32 v110, 0
	v_mov_b32_e32 v111, 0
	v_mov_b32_e32 v112, 0
	v_mov_b32_e32 v113, 0
	v_mov_b32_e32 v114, 0
	v_mov_b32_e32 v115, 0
	v_mov_b32_e32 v116, 0
	v_mov_b32_e32 v117, 0
	v_mov_b32_e32 v118, 0
	v_mov_b32_e32 v119, 0
	v_mov_b32_e32 v120, 0
	v_mov_b32_e32 v121, 0
	v_mov_b32_e32 v122, 0
	v_mov_b32_e32 v123, 0
	v_mov_b32_e32 v124, 0
	v_mov_b32_e32 v125, 0
	v_mov_b32_e32 v126, 0
	v_mov_b32_e32 v127, 0
	s_mov_b32 s1, 0
	s_waitcnt vmcnt(10)
	ds_write_b128 v241, v[160:163]
	ds_write_b128 v241, v[164:167] offset:4096
	s_waitcnt lgkmcnt(0)
	s_barrier
.Lg16_gu_k:
	s_add_i32 s8, s1, 2
	s_min_u32 s9, s8, 30
	s_lshl_b32 s96, s9, 13
	v_lshl_add_u64 v[166:167], v[188:189], 0, s[96:97]
	global_load_dwordx4 v[160:163], v[166:167], off offset:-2048
	global_load_dwordx4 v[164:167], v[166:167], off offset:2048
	ds_read_b128 v[196:199], v246 offset:0
	ds_read_b128 v[200:203], v246 offset:1024
	ds_read_b128 v[204:207], v246 offset:2048
	ds_read_b128 v[242:245], v246 offset:3072
	s_lshl_b32 s96, s9, 11
	v_lshl_add_u64 v[248:249], v[184:185], 0, s[96:97]
	v_lshl_add_u64 v[250:251], v[186:187], 0, s[96:97]
	s_waitcnt vmcnt(8) lgkmcnt(3)
	v_mfma_f32_16x16x32_bf16 v[112:115], v[128:131], v[196:199], v[112:115]
	v_mfma_f32_16x16x32_bf16 v[120:123], v[132:135], v[196:199], v[120:123]
	v_mfma_f32_16x16x32_bf16 v[80:83], v[136:139], v[196:199], v[80:83]
	v_mfma_f32_16x16x32_bf16 v[88:91], v[140:143], v[196:199], v[88:91]
	ds_read_b128 v[196:199], v246 offset:4096
	s_waitcnt lgkmcnt(3)
	v_mfma_f32_16x16x32_bf16 v[116:119], v[128:131], v[200:203], v[116:119]
	v_mfma_f32_16x16x32_bf16 v[124:127], v[132:135], v[200:203], v[124:127]
	v_mfma_f32_16x16x32_bf16 v[84:87], v[136:139], v[200:203], v[84:87]
	v_mfma_f32_16x16x32_bf16 v[92:95], v[140:143], v[200:203], v[92:95]
	ds_read_b128 v[200:203], v246 offset:5120
	s_waitcnt lgkmcnt(3)
	v_mfma_f32_16x16x32_bf16 v[96:99], v[128:131], v[204:207], v[96:99]
	v_mfma_f32_16x16x32_bf16 v[104:107], v[132:135], v[204:207], v[104:107]
	v_mfma_f32_16x16x32_bf16 v[64:67], v[136:139], v[204:207], v[64:67]
	v_mfma_f32_16x16x32_bf16 v[72:75], v[140:143], v[204:207], v[72:75]
	ds_read_b128 v[204:207], v246 offset:6144
	s_waitcnt lgkmcnt(3)
	v_mfma_f32_16x16x32_bf16 v[100:103], v[128:131], v[242:245], v[100:103]
	v_mfma_f32_16x16x32_bf16 v[108:111], v[132:135], v[242:245], v[108:111]
	v_mfma_f32_16x16x32_bf16 v[68:71], v[136:139], v[242:245], v[68:71]
	v_mfma_f32_16x16x32_bf16 v[76:79], v[140:143], v[242:245], v[76:79]
	ds_read_b128 v[242:245], v246 offset:7168
	s_waitcnt vmcnt(6)
	ds_write_b128 v241, v[168:171] offset:8192
	ds_write_b128 v241, v[172:175] offset:12288
	s_waitcnt lgkmcnt(5)
	v_mfma_f32_16x16x32_bf16 v[48:51], v[128:131], v[196:199], v[48:51]
	v_mfma_f32_16x16x32_bf16 v[56:59], v[132:135], v[196:199], v[56:59]
	v_mfma_f32_16x16x32_bf16 v[16:19], v[136:139], v[196:199], v[16:19]
	v_mfma_f32_16x16x32_bf16 v[24:27], v[140:143], v[196:199], v[24:27]
	s_waitcnt lgkmcnt(4)
	v_mfma_f32_16x16x32_bf16 v[52:55], v[128:131], v[200:203], v[52:55]
	v_mfma_f32_16x16x32_bf16 v[60:63], v[132:135], v[200:203], v[60:63]
	v_mfma_f32_16x16x32_bf16 v[20:23], v[136:139], v[200:203], v[20:23]
	v_mfma_f32_16x16x32_bf16 v[28:31], v[140:143], v[200:203], v[28:31]
	s_waitcnt lgkmcnt(3)
	v_mfma_f32_16x16x32_bf16 v[32:35], v[128:131], v[204:207], v[32:35]
	v_mfma_f32_16x16x32_bf16 v[40:43], v[132:135], v[204:207], v[40:43]
	v_mfma_f32_16x16x32_bf16 v[0:3], v[136:139], v[204:207], v[0:3]
	v_mfma_f32_16x16x32_bf16 v[8:11], v[140:143], v[204:207], v[8:11]
	s_waitcnt lgkmcnt(2)
	v_mfma_f32_16x16x32_bf16 v[36:39], v[128:131], v[242:245], v[36:39]
	v_mfma_f32_16x16x32_bf16 v[44:47], v[132:135], v[242:245], v[44:47]
	v_mfma_f32_16x16x32_bf16 v[4:7], v[136:139], v[242:245], v[4:7]
	v_mfma_f32_16x16x32_bf16 v[12:15], v[140:143], v[242:245], v[12:15]
	global_load_dwordx4 v[128:131], v[248:249], off
	global_load_dwordx4 v[132:135], v[248:249], off offset:256
	global_load_dwordx4 v[136:139], v[250:251], off
	global_load_dwordx4 v[140:143], v[250:251], off offset:256
	s_waitcnt lgkmcnt(0)
	s_barrier
	s_add_i32 s8, s1, 3
	s_min_u32 s9, s8, 31
	s_lshl_b32 s96, s9, 13
	v_lshl_add_u64 v[174:175], v[188:189], 0, s[96:97]
	global_load_dwordx4 v[168:171], v[174:175], off offset:-2048
	global_load_dwordx4 v[172:175], v[174:175], off offset:2048
	ds_read_b128 v[196:199], v246 offset:8192
	ds_read_b128 v[200:203], v246 offset:9216
	ds_read_b128 v[204:207], v246 offset:10240
	ds_read_b128 v[242:245], v246 offset:11264
	s_lshl_b32 s96, s9, 11
	v_lshl_add_u64 v[248:249], v[184:185], 0, s[96:97]
	v_lshl_add_u64 v[250:251], v[186:187], 0, s[96:97]
	s_waitcnt vmcnt(8) lgkmcnt(3)
	v_mfma_f32_16x16x32_bf16 v[112:115], v[144:147], v[196:199], v[112:115]
	v_mfma_f32_16x16x32_bf16 v[120:123], v[148:151], v[196:199], v[120:123]
	v_mfma_f32_16x16x32_bf16 v[80:83], v[152:155], v[196:199], v[80:83]
	v_mfma_f32_16x16x32_bf16 v[88:91], v[156:159], v[196:199], v[88:91]
	ds_read_b128 v[196:199], v246 offset:12288
	s_waitcnt lgkmcnt(3)
	v_mfma_f32_16x16x32_bf16 v[116:119], v[144:147], v[200:203], v[116:119]
	v_mfma_f32_16x16x32_bf16 v[124:127], v[148:151], v[200:203], v[124:127]
	v_mfma_f32_16x16x32_bf16 v[84:87], v[152:155], v[200:203], v[84:87]
	v_mfma_f32_16x16x32_bf16 v[92:95], v[156:159], v[200:203], v[92:95]
	ds_read_b128 v[200:203], v246 offset:13312
	s_waitcnt lgkmcnt(3)
	v_mfma_f32_16x16x32_bf16 v[96:99], v[144:147], v[204:207], v[96:99]
	v_mfma_f32_16x16x32_bf16 v[104:107], v[148:151], v[204:207], v[104:107]
	v_mfma_f32_16x16x32_bf16 v[64:67], v[152:155], v[204:207], v[64:67]
	v_mfma_f32_16x16x32_bf16 v[72:75], v[156:159], v[204:207], v[72:75]
	ds_read_b128 v[204:207], v246 offset:14336
	s_waitcnt lgkmcnt(3)
	v_mfma_f32_16x16x32_bf16 v[100:103], v[144:147], v[242:245], v[100:103]
	v_mfma_f32_16x16x32_bf16 v[108:111], v[148:151], v[242:245], v[108:111]
	v_mfma_f32_16x16x32_bf16 v[68:71], v[152:155], v[242:245], v[68:71]
	v_mfma_f32_16x16x32_bf16 v[76:79], v[156:159], v[242:245], v[76:79]
	ds_read_b128 v[242:245], v246 offset:15360
	s_waitcnt vmcnt(6)
	ds_write_b128 v241, v[160:163] offset:0
	ds_write_b128 v241, v[164:167] offset:4096
	s_waitcnt lgkmcnt(5)
	v_mfma_f32_16x16x32_bf16 v[48:51], v[144:147], v[196:199], v[48:51]
	v_mfma_f32_16x16x32_bf16 v[56:59], v[148:151], v[196:199], v[56:59]
	v_mfma_f32_16x16x32_bf16 v[16:19], v[152:155], v[196:199], v[16:19]
	v_mfma_f32_16x16x32_bf16 v[24:27], v[156:159], v[196:199], v[24:27]
	s_waitcnt lgkmcnt(4)
	v_mfma_f32_16x16x32_bf16 v[52:55], v[144:147], v[200:203], v[52:55]
	v_mfma_f32_16x16x32_bf16 v[60:63], v[148:151], v[200:203], v[60:63]
	v_mfma_f32_16x16x32_bf16 v[20:23], v[152:155], v[200:203], v[20:23]
	v_mfma_f32_16x16x32_bf16 v[28:31], v[156:159], v[200:203], v[28:31]
	s_waitcnt lgkmcnt(3)
	v_mfma_f32_16x16x32_bf16 v[32:35], v[144:147], v[204:207], v[32:35]
	v_mfma_f32_16x16x32_bf16 v[40:43], v[148:151], v[204:207], v[40:43]
	v_mfma_f32_16x16x32_bf16 v[0:3], v[152:155], v[204:207], v[0:3]
	v_mfma_f32_16x16x32_bf16 v[8:11], v[156:159], v[204:207], v[8:11]
	s_waitcnt lgkmcnt(2)
	v_mfma_f32_16x16x32_bf16 v[36:39], v[144:147], v[242:245], v[36:39]
	v_mfma_f32_16x16x32_bf16 v[44:47], v[148:151], v[242:245], v[44:47]
	v_mfma_f32_16x16x32_bf16 v[4:7], v[152:155], v[242:245], v[4:7]
	v_mfma_f32_16x16x32_bf16 v[12:15], v[156:159], v[242:245], v[12:15]
	global_load_dwordx4 v[144:147], v[248:249], off
	global_load_dwordx4 v[148:151], v[248:249], off offset:256
	global_load_dwordx4 v[152:155], v[250:251], off
	global_load_dwordx4 v[156:159], v[250:251], off offset:256
	s_add_i32 s1, s1, 2
	s_cmp_lt_u32 s1, 32
	s_waitcnt lgkmcnt(0)
	s_barrier
	s_cbranch_scc1 .Lg16_gu_k
	s_nop 7
	v_permlane16_swap_b32_e32 v112, v116
	v_permlane16_swap_b32_e32 v113, v117
	v_permlane16_swap_b32_e32 v114, v118
	v_permlane16_swap_b32_e32 v115, v119
	v_permlane16_swap_b32_e32 v120, v124
	v_permlane16_swap_b32_e32 v121, v125
	v_permlane16_swap_b32_e32 v122, v126
	v_permlane16_swap_b32_e32 v123, v127
	v_permlane16_swap_b32_e32 v96, v100
	v_permlane16_swap_b32_e32 v97, v101
	v_permlane16_swap_b32_e32 v98, v102
	v_permlane16_swap_b32_e32 v99, v103
	v_permlane16_swap_b32_e32 v104, v108
	v_permlane16_swap_b32_e32 v105, v109
	v_permlane16_swap_b32_e32 v106, v110
	v_permlane16_swap_b32_e32 v107, v111
	v_permlane16_swap_b32_e32 v48, v52
	v_permlane16_swap_b32_e32 v49, v53
	v_permlane16_swap_b32_e32 v50, v54
	v_permlane16_swap_b32_e32 v51, v55
	v_permlane16_swap_b32_e32 v56, v60
	v_permlane16_swap_b32_e32 v57, v61
	v_permlane16_swap_b32_e32 v58, v62
	v_permlane16_swap_b32_e32 v59, v63
	v_permlane16_swap_b32_e32 v32, v36
	v_permlane16_swap_b32_e32 v33, v37
	v_permlane16_swap_b32_e32 v34, v38
	v_permlane16_swap_b32_e32 v35, v39
	v_permlane16_swap_b32_e32 v40, v44
	v_permlane16_swap_b32_e32 v41, v45
	v_permlane16_swap_b32_e32 v42, v46
	v_permlane16_swap_b32_e32 v43, v47
	v_permlane16_swap_b32_e32 v80, v84
	v_permlane16_swap_b32_e32 v81, v85
	v_permlane16_swap_b32_e32 v82, v86
	v_permlane16_swap_b32_e32 v83, v87
	v_permlane16_swap_b32_e32 v88, v92
	v_permlane16_swap_b32_e32 v89, v93
	v_permlane16_swap_b32_e32 v90, v94
	v_permlane16_swap_b32_e32 v91, v95
	v_permlane16_swap_b32_e32 v64, v68
	v_permlane16_swap_b32_e32 v65, v69
	v_permlane16_swap_b32_e32 v66, v70
	v_permlane16_swap_b32_e32 v67, v71
	v_permlane16_swap_b32_e32 v72, v76
	v_permlane16_swap_b32_e32 v73, v77
	v_permlane16_swap_b32_e32 v74, v78
	v_permlane16_swap_b32_e32 v75, v79
	v_permlane16_swap_b32_e32 v16, v20
	v_permlane16_swap_b32_e32 v17, v21
	v_permlane16_swap_b32_e32 v18, v22
	v_permlane16_swap_b32_e32 v19, v23
	v_permlane16_swap_b32_e32 v24, v28
	v_permlane16_swap_b32_e32 v25, v29
	v_permlane16_swap_b32_e32 v26, v30
	v_permlane16_swap_b32_e32 v27, v31
	v_permlane16_swap_b32_e32 v0, v4
	v_permlane16_swap_b32_e32 v1, v5
	v_permlane16_swap_b32_e32 v2, v6
	v_permlane16_swap_b32_e32 v3, v7
	v_permlane16_swap_b32_e32 v8, v12
	v_permlane16_swap_b32_e32 v9, v13
	v_permlane16_swap_b32_e32 v10, v14
	v_permlane16_swap_b32_e32 v11, v15
	v_permlane32_swap_b32_e32 v112, v116
	v_permlane32_swap_b32_e32 v113, v117
	v_permlane32_swap_b32_e32 v114, v118
	v_permlane32_swap_b32_e32 v115, v119
	v_permlane32_swap_b32_e32 v120, v124
	v_permlane32_swap_b32_e32 v121, v125
	v_permlane32_swap_b32_e32 v122, v126
	v_permlane32_swap_b32_e32 v123, v127
	v_permlane32_swap_b32_e32 v96, v100
	v_permlane32_swap_b32_e32 v97, v101
	v_permlane32_swap_b32_e32 v98, v102
	v_permlane32_swap_b32_e32 v99, v103
	v_permlane32_swap_b32_e32 v104, v108
	v_permlane32_swap_b32_e32 v105, v109
	v_permlane32_swap_b32_e32 v106, v110
	v_permlane32_swap_b32_e32 v107, v111
	v_permlane32_swap_b32_e32 v48, v52
	v_permlane32_swap_b32_e32 v49, v53
	v_permlane32_swap_b32_e32 v50, v54
	v_permlane32_swap_b32_e32 v51, v55
	v_permlane32_swap_b32_e32 v56, v60
	v_permlane32_swap_b32_e32 v57, v61
	v_permlane32_swap_b32_e32 v58, v62
	v_permlane32_swap_b32_e32 v59, v63
	v_permlane32_swap_b32_e32 v32, v36
	v_permlane32_swap_b32_e32 v33, v37
	v_permlane32_swap_b32_e32 v34, v38
	v_permlane32_swap_b32_e32 v35, v39
	v_permlane32_swap_b32_e32 v40, v44
	v_permlane32_swap_b32_e32 v41, v45
	v_permlane32_swap_b32_e32 v42, v46
	v_permlane32_swap_b32_e32 v43, v47
	v_permlane32_swap_b32_e32 v80, v84
	v_permlane32_swap_b32_e32 v81, v85
	v_permlane32_swap_b32_e32 v82, v86
	v_permlane32_swap_b32_e32 v83, v87
	v_permlane32_swap_b32_e32 v88, v92
	v_permlane32_swap_b32_e32 v89, v93
	v_permlane32_swap_b32_e32 v90, v94
	v_permlane32_swap_b32_e32 v91, v95
	v_permlane32_swap_b32_e32 v64, v68
	v_permlane32_swap_b32_e32 v65, v69
	v_permlane32_swap_b32_e32 v66, v70
	v_permlane32_swap_b32_e32 v67, v71
	v_permlane32_swap_b32_e32 v72, v76
	v_permlane32_swap_b32_e32 v73, v77
	v_permlane32_swap_b32_e32 v74, v78
	v_permlane32_swap_b32_e32 v75, v79
	v_permlane32_swap_b32_e32 v16, v20
	v_permlane32_swap_b32_e32 v17, v21
	v_permlane32_swap_b32_e32 v18, v22
	v_permlane32_swap_b32_e32 v19, v23
	v_permlane32_swap_b32_e32 v24, v28
	v_permlane32_swap_b32_e32 v25, v29
	v_permlane32_swap_b32_e32 v26, v30
	v_permlane32_swap_b32_e32 v27, v31
	v_permlane32_swap_b32_e32 v0, v4
	v_permlane32_swap_b32_e32 v1, v5
	v_permlane32_swap_b32_e32 v2, v6
	v_permlane32_swap_b32_e32 v3, v7
	v_permlane32_swap_b32_e32 v8, v12
	v_permlane32_swap_b32_e32 v9, v13
	v_permlane32_swap_b32_e32 v10, v14
	v_permlane32_swap_b32_e32 v11, v15
	s_waitcnt vmcnt(0)
	v_mul_f32_e32 v133, 0xbfb8aa3b, v112
	v_exp_f32_e32 v133, v133
	s_movk_i32 s1, 0x2400
	v_mul_lo_u32 v128, v238, s1
	v_lshl_or_b32 v131, s0, 6, v181
	v_add_f32_e32 v133, 1.0, v133
	v_lshl_or_b32 v132, v239, 1, v128
	v_and_b32_e32 v129, 0xffffffc0, v237
	v_lshl_or_b32 v128, v181, 1, v128
	v_rcp_f32_e32 v135, v133
	s_nop 0
	v_mul_f32_e32 v112, v112, v135
	v_mul_f32_e32 v96, v96, v112
	v_cvt_pk_bf16_f32 v112, v96, s0
	s_movk_i32 s0, 0x240
	v_mad_u32_u24 v96, v183, s0, v132
	ds_write_b16 v96, v112
	v_mul_f32_e32 v112, 0xbfb8aa3b, v113
	v_exp_f32_e32 v112, v112
	v_lshl_add_u32 v130, s7, 8, v129
	v_lshrrev_b32_e32 v129, 2, v240
	v_mad_u32_u24 v128, v129, s42, v128
	v_add_f32_e32 v112, 1.0, v112
	v_rcp_f32_e32 v133, v112
	s_nop 0
	v_mul_f32_e32 v112, v113, v133
	v_mul_f32_e32 v97, v97, v112
	v_cvt_pk_bf16_f32 v97, v97, s0
	ds_write_b16 v96, v97 offset:144
	v_mul_f32_e32 v97, 0xbfb8aa3b, v114
	v_exp_f32_e32 v97, v97
	s_nop 0
	v_add_f32_e32 v97, 1.0, v97
	v_rcp_f32_e32 v113, v97
	s_nop 0
	v_mul_f32_e32 v97, v114, v113
	v_mul_f32_e32 v97, v98, v97
	v_cvt_pk_bf16_f32 v97, v97, s0
	ds_write_b16 v96, v97 offset:288
	v_mul_f32_e32 v97, 0xbfb8aa3b, v115
	v_exp_f32_e32 v97, v97
	s_nop 0
	v_add_f32_e32 v97, 1.0, v97
	v_rcp_f32_e32 v112, v97
	s_nop 0
	v_mul_f32_e32 v97, v115, v112
	v_mul_f32_e32 v97, v99, v97
	v_cvt_pk_bf16_f32 v97, v97, s0
	ds_write_b16 v96, v97 offset:432
	v_mul_f32_e32 v97, 0xbfb8aa3b, v116
	v_exp_f32_e32 v97, v97
	s_nop 0
	v_add_f32_e32 v97, 1.0, v97
	v_rcp_f32_e32 v99, v97
	s_nop 0
	v_mul_f32_e32 v97, v116, v99
	v_mul_f32_e32 v97, v100, v97
	v_cvt_pk_bf16_f32 v97, v97, s0
	ds_write_b16 v96, v97 offset:1152
	v_mul_f32_e32 v97, 0xbfb8aa3b, v117
	v_exp_f32_e32 v97, v97
	s_nop 0
	v_add_f32_e32 v97, 1.0, v97
	v_rcp_f32_e32 v99, v97
	s_nop 0
	v_mul_f32_e32 v97, v117, v99
	v_mul_f32_e32 v97, v101, v97
	v_cvt_pk_bf16_f32 v97, v97, s0
	ds_write_b16 v96, v97 offset:1296
	v_mul_f32_e32 v97, 0xbfb8aa3b, v118
	v_exp_f32_e32 v97, v97
	s_nop 0
	v_add_f32_e32 v97, 1.0, v97
	v_rcp_f32_e32 v99, v97
	s_nop 0
	v_mul_f32_e32 v97, v118, v99
	v_mul_f32_e32 v97, v102, v97
	v_cvt_pk_bf16_f32 v97, v97, s0
	ds_write_b16 v96, v97 offset:1440
	v_mul_f32_e32 v97, 0xbfb8aa3b, v119
	v_exp_f32_e32 v97, v97
	s_nop 0
	v_add_f32_e32 v97, 1.0, v97
	v_rcp_f32_e32 v99, v97
	s_nop 0
	v_mul_f32_e32 v97, v119, v99
	v_mul_f32_e32 v97, v103, v97
	v_cvt_pk_bf16_f32 v97, v97, s0
	ds_write_b16 v96, v97 offset:1584
	v_mul_f32_e32 v97, 0xbfb8aa3b, v120
	v_exp_f32_e32 v97, v97
	s_nop 0
	v_add_f32_e32 v97, 1.0, v97
	v_rcp_f32_e32 v99, v97
	s_nop 0
	v_mul_f32_e32 v97, v120, v99
	v_mul_f32_e32 v97, v104, v97
	v_cvt_pk_bf16_f32 v97, v97, s0
	ds_write_b16 v96, v97 offset:2304
	v_mul_f32_e32 v97, 0xbfb8aa3b, v121
	v_exp_f32_e32 v97, v97
	s_nop 0
	v_add_f32_e32 v97, 1.0, v97
	v_rcp_f32_e32 v99, v97
	s_nop 0
	v_mul_f32_e32 v97, v121, v99
	v_mul_f32_e32 v97, v105, v97
	v_cvt_pk_bf16_f32 v97, v97, s0
	ds_write_b16 v96, v97 offset:2448
	v_mul_f32_e32 v97, 0xbfb8aa3b, v122
	v_exp_f32_e32 v97, v97
	s_nop 0
	v_add_f32_e32 v97, 1.0, v97
	v_rcp_f32_e32 v99, v97
	s_nop 0
	v_mul_f32_e32 v97, v122, v99
	v_mul_f32_e32 v97, v106, v97
	v_cvt_pk_bf16_f32 v97, v97, s0
	ds_write_b16 v96, v97 offset:2592
	v_mul_f32_e32 v97, 0xbfb8aa3b, v123
	v_exp_f32_e32 v97, v97
	s_nop 0
	v_add_f32_e32 v97, 1.0, v97
	v_rcp_f32_e32 v99, v97
	s_nop 0
	v_mul_f32_e32 v97, v123, v99
	v_mul_f32_e32 v97, v107, v97
	v_cvt_pk_bf16_f32 v97, v97, s0
	ds_write_b16 v96, v97 offset:2736
	v_mul_f32_e32 v97, 0xbfb8aa3b, v124
	v_exp_f32_e32 v97, v97
	s_nop 0
	v_add_f32_e32 v97, 1.0, v97
	v_rcp_f32_e32 v99, v97
	s_nop 0
	v_mul_f32_e32 v97, v124, v99
	v_mul_f32_e32 v97, v108, v97
	v_cvt_pk_bf16_f32 v97, v97, s0
	ds_write_b16 v96, v97 offset:3456
	v_mul_f32_e32 v97, 0xbfb8aa3b, v125
	v_exp_f32_e32 v97, v97
	s_nop 0
	v_add_f32_e32 v97, 1.0, v97
	v_rcp_f32_e32 v99, v97
	s_nop 0
	v_mul_f32_e32 v97, v125, v99
	v_mul_f32_e32 v97, v109, v97
	v_cvt_pk_bf16_f32 v97, v97, s0
	ds_write_b16 v96, v97 offset:3600
	v_mul_f32_e32 v97, 0xbfb8aa3b, v126
	v_exp_f32_e32 v97, v97
	s_nop 0
	v_add_f32_e32 v97, 1.0, v97
	v_rcp_f32_e32 v99, v97
	s_nop 0
	v_mul_f32_e32 v97, v126, v99
	v_mul_f32_e32 v97, v110, v97
	v_cvt_pk_bf16_f32 v97, v97, s0
	ds_write_b16 v96, v97 offset:3744
	v_mul_f32_e32 v97, 0xbfb8aa3b, v127
	v_exp_f32_e32 v97, v97
	s_nop 0
	v_add_f32_e32 v97, 1.0, v97
	v_rcp_f32_e32 v99, v97
	s_nop 0
	v_mul_f32_e32 v97, v127, v99
	v_mul_f32_e32 v97, v111, v97
	v_cvt_pk_bf16_f32 v97, v97, s0
	ds_write_b16 v96, v97 offset:3888
	v_mul_f32_e32 v97, 0xbfb8aa3b, v80
	v_exp_f32_e32 v97, v97
	s_nop 0
	v_add_f32_e32 v97, 1.0, v97
	v_rcp_f32_e32 v99, v97
	s_nop 0
	v_mul_f32_e32 v80, v80, v99
	v_mul_f32_e32 v64, v64, v80
	v_cvt_pk_bf16_f32 v64, v64, s0
	ds_write_b16 v96, v64 offset:4608
	v_mul_f32_e32 v64, 0xbfb8aa3b, v81
	v_exp_f32_e32 v64, v64
	s_nop 0
	v_add_f32_e32 v64, 1.0, v64
	v_rcp_f32_e32 v97, v64
	s_nop 0
	v_mul_f32_e32 v64, v81, v97
	v_mul_f32_e32 v64, v65, v64
	v_cvt_pk_bf16_f32 v64, v64, s0
	ds_write_b16 v96, v64 offset:4752
	v_mul_f32_e32 v64, 0xbfb8aa3b, v82
	v_exp_f32_e32 v64, v64
	s_nop 0
	v_add_f32_e32 v64, 1.0, v64
	v_rcp_f32_e32 v80, v64
	s_nop 0
	v_mul_f32_e32 v64, v82, v80
	v_mul_f32_e32 v64, v66, v64
	v_cvt_pk_bf16_f32 v64, v64, s0
	ds_write_b16 v96, v64 offset:4896
	v_mul_f32_e32 v64, 0xbfb8aa3b, v83
	v_exp_f32_e32 v64, v64
	s_nop 0
	v_add_f32_e32 v64, 1.0, v64
	v_rcp_f32_e32 v66, v64
	s_nop 0
	v_mul_f32_e32 v64, v83, v66
	v_mul_f32_e32 v64, v67, v64
	v_cvt_pk_bf16_f32 v64, v64, s0
	ds_write_b16 v96, v64 offset:5040
	v_mul_f32_e32 v64, 0xbfb8aa3b, v84
	v_exp_f32_e32 v64, v64
	s_nop 0
	v_add_f32_e32 v64, 1.0, v64
	v_rcp_f32_e32 v66, v64
	s_nop 0
	v_mul_f32_e32 v64, v84, v66
	v_mul_f32_e32 v64, v68, v64
	v_cvt_pk_bf16_f32 v64, v64, s0
	ds_write_b16 v96, v64 offset:5760
	v_mul_f32_e32 v64, 0xbfb8aa3b, v85
	v_exp_f32_e32 v64, v64
	s_nop 0
	v_add_f32_e32 v64, 1.0, v64
	v_rcp_f32_e32 v66, v64
	s_nop 0
	v_mul_f32_e32 v64, v85, v66
	v_mul_f32_e32 v64, v69, v64
	v_cvt_pk_bf16_f32 v64, v64, s0
	ds_write_b16 v96, v64 offset:5904
	v_mul_f32_e32 v64, 0xbfb8aa3b, v86
	v_exp_f32_e32 v64, v64
	s_nop 0
	v_add_f32_e32 v64, 1.0, v64
	v_rcp_f32_e32 v66, v64
	s_nop 0
	v_mul_f32_e32 v64, v86, v66
	v_mul_f32_e32 v64, v70, v64
	v_cvt_pk_bf16_f32 v64, v64, s0
	ds_write_b16 v96, v64 offset:6048
	v_mul_f32_e32 v64, 0xbfb8aa3b, v87
	v_exp_f32_e32 v64, v64
	s_nop 0
	v_add_f32_e32 v64, 1.0, v64
	v_rcp_f32_e32 v66, v64
	s_nop 0
	v_mul_f32_e32 v64, v87, v66
	v_mul_f32_e32 v64, v71, v64
	v_cvt_pk_bf16_f32 v64, v64, s0
	ds_write_b16 v96, v64 offset:6192
	v_mul_f32_e32 v64, 0xbfb8aa3b, v88
	v_exp_f32_e32 v64, v64
	v_ashrrev_i32_e32 v71, 5, v130
	v_or_b32_e32 v70, 1, v71
	v_add_f32_e32 v64, 1.0, v64
	v_rcp_f32_e32 v66, v64
	s_nop 0
	v_mul_f32_e32 v64, v88, v66
	v_mul_f32_e32 v64, v72, v64
	v_cvt_pk_bf16_f32 v64, v64, s0
	ds_write_b16 v96, v64 offset:6912
	v_mul_f32_e32 v64, 0xbfb8aa3b, v89
	v_exp_f32_e32 v64, v64
	s_nop 0
	v_add_f32_e32 v64, 1.0, v64
	v_rcp_f32_e32 v66, v64
	s_nop 0
	v_mul_f32_e32 v64, v89, v66
	v_mul_f32_e32 v64, v73, v64
	v_cvt_pk_bf16_f32 v64, v64, s0
	ds_write_b16 v96, v64 offset:7056
	v_mul_f32_e32 v64, 0xbfb8aa3b, v90
	v_exp_f32_e32 v64, v64
	s_nop 0
	v_add_f32_e32 v64, 1.0, v64
	v_rcp_f32_e32 v66, v64
	s_nop 0
	v_mul_f32_e32 v64, v90, v66
	v_mul_f32_e32 v64, v74, v64
	v_cvt_pk_bf16_f32 v64, v64, s0
	ds_write_b16 v96, v64 offset:7200
	v_mul_f32_e32 v64, 0xbfb8aa3b, v91
	v_exp_f32_e32 v64, v64
	s_nop 0
	v_add_f32_e32 v64, 1.0, v64
	v_rcp_f32_e32 v66, v64
	s_nop 0
	v_mul_f32_e32 v64, v91, v66
	v_mul_f32_e32 v64, v75, v64
	v_cvt_pk_bf16_f32 v64, v64, s0
	ds_write_b16 v96, v64 offset:7344
	v_mul_f32_e32 v64, 0xbfb8aa3b, v92
	v_exp_f32_e32 v64, v64
	s_nop 0
	v_add_f32_e32 v64, 1.0, v64
	v_rcp_f32_e32 v66, v64
	s_nop 0
	v_mul_f32_e32 v64, v92, v66
	v_mul_f32_e32 v64, v76, v64
	v_cvt_pk_bf16_f32 v64, v64, s0
	ds_write_b16 v96, v64 offset:8064
	v_mul_f32_e32 v64, 0xbfb8aa3b, v93
	v_exp_f32_e32 v64, v64
	s_nop 0
	v_add_f32_e32 v64, 1.0, v64
	v_rcp_f32_e32 v66, v64
	s_nop 0
	v_mul_f32_e32 v64, v93, v66
	v_mul_f32_e32 v64, v77, v64
	v_cvt_pk_bf16_f32 v64, v64, s0
	ds_write_b16 v96, v64 offset:8208
	v_mul_f32_e32 v64, 0xbfb8aa3b, v94
	v_exp_f32_e32 v64, v64
	s_nop 0
	v_add_f32_e32 v64, 1.0, v64
	v_rcp_f32_e32 v66, v64
	s_nop 0
	v_mul_f32_e32 v64, v94, v66
	v_mul_f32_e32 v64, v78, v64
	v_cvt_pk_bf16_f32 v64, v64, s0
	ds_write_b16 v96, v64 offset:8352
	v_mul_f32_e32 v64, 0xbfb8aa3b, v95
	v_exp_f32_e32 v64, v64
	s_nop 0
	v_add_f32_e32 v64, 1.0, v64
	v_rcp_f32_e32 v66, v64
	s_nop 0
	v_mul_f32_e32 v64, v95, v66
	v_mul_f32_e32 v64, v79, v64
	v_cvt_pk_bf16_f32 v64, v64, s0
	ds_write_b16 v96, v64 offset:8496
	v_ashrrev_i32_e32 v68, 4, v131
	s_waitcnt lgkmcnt(0)
	v_ashrrev_i32_e32 v69, 31, v68
	ds_read_b128 v[72:75], v128
	v_mad_i64_i32 v[64:65], s[0:1], v71, s23, v[68:69]
	v_lshlrev_b64 v[64:65], 10, v[64:65]
	v_lshlrev_b32_e32 v66, 6, v181
	v_lshl_add_u64 v[64:65], s[66:67], 0, v[64:65]
	v_and_b32_e32 v176, 0x200, v66
	v_lshl_add_u64 v[76:77], v[64:65], 0, v[176:177]
	v_lshlrev_b32_e32 v66, 4, v129
	v_mov_b32_e32 v67, v177
	v_lshl_add_u64 v[64:65], v[76:77], 0, v[66:67]
	s_waitcnt lgkmcnt(0)
	global_store_dwordx4 v[64:65], v[72:75], off
	ds_read_b128 v[72:75], v128 offset:2304
	v_or_b32_e32 v64, 0x100, v66
	v_mov_b32_e32 v65, v177
	v_lshl_add_u64 v[76:77], v[76:77], 0, v[64:65]
	s_waitcnt lgkmcnt(0)
	global_store_dwordx4 v[76:77], v[72:75], off
	ds_read_b128 v[72:75], v128 offset:4608
	v_mad_i64_i32 v[76:77], s[0:1], v70, s23, v[68:69]
	v_lshlrev_b64 v[76:77], 10, v[76:77]
	v_lshl_add_u64 v[76:77], s[66:67], 0, v[76:77]
	v_lshl_add_u64 v[76:77], v[76:77], 0, v[176:177]
	v_lshl_add_u64 v[78:79], v[76:77], 0, v[66:67]
	v_mul_f32_e32 v69, 0xbfb8aa3b, v48
	s_waitcnt lgkmcnt(0)
	global_store_dwordx4 v[78:79], v[72:75], off
	ds_read_b128 v[72:75], v128 offset:6912
	v_exp_f32_e32 v69, v69
	v_lshl_add_u64 v[76:77], v[76:77], 0, v[64:65]
	v_add_f32_e32 v69, 1.0, v69
	s_waitcnt lgkmcnt(0)
	global_store_dwordx4 v[76:77], v[72:75], off
	s_waitcnt lgkmcnt(0)
	s_nop 1
	v_rcp_f32_e32 v73, v69
	s_nop 0
	v_mul_f32_e32 v48, v48, v73
	v_mul_f32_e32 v32, v32, v48
	v_cvt_pk_bf16_f32 v32, v32, s0
	ds_write_b16 v96, v32
	v_mul_f32_e32 v32, 0xbfb8aa3b, v49
	v_exp_f32_e32 v32, v32
	s_nop 0
	v_add_f32_e32 v32, 1.0, v32
	v_rcp_f32_e32 v69, v32
	s_nop 0
	v_mul_f32_e32 v32, v49, v69
	v_mul_f32_e32 v32, v33, v32
	v_cvt_pk_bf16_f32 v32, v32, s0
	ds_write_b16 v96, v32 offset:144
	v_mul_f32_e32 v32, 0xbfb8aa3b, v50
	v_exp_f32_e32 v32, v32
	s_nop 0
	v_add_f32_e32 v32, 1.0, v32
	v_rcp_f32_e32 v48, v32
	s_nop 0
	v_mul_f32_e32 v32, v50, v48
	v_mul_f32_e32 v32, v34, v32
	v_cvt_pk_bf16_f32 v32, v32, s0
	ds_write_b16 v96, v32 offset:288
	v_mul_f32_e32 v32, 0xbfb8aa3b, v51
	v_exp_f32_e32 v32, v32
	s_nop 0
	v_add_f32_e32 v32, 1.0, v32
	v_rcp_f32_e32 v34, v32
	s_nop 0
	v_mul_f32_e32 v32, v51, v34
	v_mul_f32_e32 v32, v35, v32
	v_cvt_pk_bf16_f32 v32, v32, s0
	ds_write_b16 v96, v32 offset:432
	v_mul_f32_e32 v32, 0xbfb8aa3b, v52
	v_exp_f32_e32 v32, v32
	s_nop 0
	v_add_f32_e32 v32, 1.0, v32
	v_rcp_f32_e32 v34, v32
	s_nop 0
	v_mul_f32_e32 v32, v52, v34
	v_mul_f32_e32 v32, v36, v32
	v_cvt_pk_bf16_f32 v32, v32, s0
	ds_write_b16 v96, v32 offset:1152
	v_mul_f32_e32 v32, 0xbfb8aa3b, v53
	v_exp_f32_e32 v32, v32
	s_nop 0
	v_add_f32_e32 v32, 1.0, v32
	v_rcp_f32_e32 v34, v32
	s_nop 0
	v_mul_f32_e32 v32, v53, v34
	v_mul_f32_e32 v32, v37, v32
	v_cvt_pk_bf16_f32 v32, v32, s0
	ds_write_b16 v96, v32 offset:1296
	v_mul_f32_e32 v32, 0xbfb8aa3b, v54
	v_exp_f32_e32 v32, v32
	s_nop 0
	v_add_f32_e32 v32, 1.0, v32
	v_rcp_f32_e32 v34, v32
	s_nop 0
	v_mul_f32_e32 v32, v54, v34
	v_mul_f32_e32 v32, v38, v32
	v_cvt_pk_bf16_f32 v32, v32, s0
	ds_write_b16 v96, v32 offset:1440
	v_mul_f32_e32 v32, 0xbfb8aa3b, v55
	v_exp_f32_e32 v32, v32
	s_nop 0
	v_add_f32_e32 v32, 1.0, v32
	v_rcp_f32_e32 v34, v32
	s_nop 0
	v_mul_f32_e32 v32, v55, v34
	v_mul_f32_e32 v32, v39, v32
	v_cvt_pk_bf16_f32 v32, v32, s0
	ds_write_b16 v96, v32 offset:1584
	v_mul_f32_e32 v32, 0xbfb8aa3b, v56
	v_exp_f32_e32 v32, v32
	s_nop 0
	v_add_f32_e32 v32, 1.0, v32
	v_rcp_f32_e32 v34, v32
	s_nop 0
	v_mul_f32_e32 v32, v56, v34
	v_mul_f32_e32 v32, v40, v32
	v_cvt_pk_bf16_f32 v32, v32, s0
	ds_write_b16 v96, v32 offset:2304
	v_mul_f32_e32 v32, 0xbfb8aa3b, v57
	v_exp_f32_e32 v32, v32
	s_nop 0
	v_add_f32_e32 v32, 1.0, v32
	v_rcp_f32_e32 v34, v32
	s_nop 0
	v_mul_f32_e32 v32, v57, v34
	v_mul_f32_e32 v32, v41, v32
	v_cvt_pk_bf16_f32 v32, v32, s0
	ds_write_b16 v96, v32 offset:2448
	v_mul_f32_e32 v32, 0xbfb8aa3b, v58
	v_exp_f32_e32 v32, v32
	s_nop 0
	v_add_f32_e32 v32, 1.0, v32
	v_rcp_f32_e32 v34, v32
	s_nop 0
	v_mul_f32_e32 v32, v58, v34
	v_mul_f32_e32 v32, v42, v32
	v_cvt_pk_bf16_f32 v32, v32, s0
	ds_write_b16 v96, v32 offset:2592
	v_mul_f32_e32 v32, 0xbfb8aa3b, v59
	v_exp_f32_e32 v32, v32
	s_nop 0
	v_add_f32_e32 v32, 1.0, v32
	v_rcp_f32_e32 v34, v32
	s_nop 0
	v_mul_f32_e32 v32, v59, v34
	v_mul_f32_e32 v32, v43, v32
	v_cvt_pk_bf16_f32 v32, v32, s0
	ds_write_b16 v96, v32 offset:2736
	v_mul_f32_e32 v32, 0xbfb8aa3b, v60
	v_exp_f32_e32 v32, v32
	s_nop 0
	v_add_f32_e32 v32, 1.0, v32
	v_rcp_f32_e32 v34, v32
	s_nop 0
	v_mul_f32_e32 v32, v60, v34
	v_mul_f32_e32 v32, v44, v32
	v_cvt_pk_bf16_f32 v32, v32, s0
	ds_write_b16 v96, v32 offset:3456
	v_mul_f32_e32 v32, 0xbfb8aa3b, v61
	v_exp_f32_e32 v32, v32
	s_nop 0
	v_add_f32_e32 v32, 1.0, v32
	v_rcp_f32_e32 v34, v32
	s_nop 0
	v_mul_f32_e32 v32, v61, v34
	v_mul_f32_e32 v32, v45, v32
	v_cvt_pk_bf16_f32 v32, v32, s0
	ds_write_b16 v96, v32 offset:3600
	v_mul_f32_e32 v32, 0xbfb8aa3b, v62
	v_exp_f32_e32 v32, v32
	s_nop 0
	v_add_f32_e32 v32, 1.0, v32
	v_rcp_f32_e32 v34, v32
	s_nop 0
	v_mul_f32_e32 v32, v62, v34
	v_mul_f32_e32 v32, v46, v32
	v_cvt_pk_bf16_f32 v32, v32, s0
	ds_write_b16 v96, v32 offset:3744
	v_mul_f32_e32 v32, 0xbfb8aa3b, v63
	v_exp_f32_e32 v32, v32
	s_nop 0
	v_add_f32_e32 v32, 1.0, v32
	v_rcp_f32_e32 v34, v32
	s_nop 0
	v_mul_f32_e32 v32, v63, v34
	v_mul_f32_e32 v32, v47, v32
	v_cvt_pk_bf16_f32 v32, v32, s0
	ds_write_b16 v96, v32 offset:3888
	v_mul_f32_e32 v32, 0xbfb8aa3b, v16
	v_exp_f32_e32 v32, v32
	s_nop 0
	v_add_f32_e32 v32, 1.0, v32
	v_rcp_f32_e32 v34, v32
	s_nop 0
	v_mul_f32_e32 v16, v16, v34
	v_mul_f32_e32 v0, v0, v16
	v_cvt_pk_bf16_f32 v0, v0, s0
	ds_write_b16 v96, v0 offset:4608
	v_mul_f32_e32 v0, 0xbfb8aa3b, v17
	v_exp_f32_e32 v0, v0
	s_nop 0
	v_add_f32_e32 v0, 1.0, v0
	v_rcp_f32_e32 v32, v0
	s_nop 0
	v_mul_f32_e32 v0, v17, v32
	v_mul_f32_e32 v0, v1, v0
	v_cvt_pk_bf16_f32 v0, v0, s0
	ds_write_b16 v96, v0 offset:4752
	v_mul_f32_e32 v0, 0xbfb8aa3b, v18
	v_exp_f32_e32 v0, v0
	s_nop 0
	v_add_f32_e32 v0, 1.0, v0
	v_rcp_f32_e32 v16, v0
	s_nop 0
	v_mul_f32_e32 v0, v18, v16
	v_mul_f32_e32 v0, v2, v0
	v_cvt_pk_bf16_f32 v0, v0, s0
	ds_write_b16 v96, v0 offset:4896
	v_mul_f32_e32 v0, 0xbfb8aa3b, v19
	v_exp_f32_e32 v0, v0
	s_nop 0
	v_add_f32_e32 v0, 1.0, v0
	v_rcp_f32_e32 v2, v0
	s_nop 0
	v_mul_f32_e32 v0, v19, v2
	v_mul_f32_e32 v0, v3, v0
	v_cvt_pk_bf16_f32 v0, v0, s0
	ds_write_b16 v96, v0 offset:5040
	v_mul_f32_e32 v0, 0xbfb8aa3b, v20
	v_exp_f32_e32 v0, v0
	s_nop 0
	v_add_f32_e32 v0, 1.0, v0
	v_rcp_f32_e32 v2, v0
	s_nop 0
	v_mul_f32_e32 v0, v20, v2
	v_mul_f32_e32 v0, v4, v0
	v_cvt_pk_bf16_f32 v0, v0, s0
	ds_write_b16 v96, v0 offset:5760
	v_mul_f32_e32 v0, 0xbfb8aa3b, v21
	v_exp_f32_e32 v0, v0
	s_nop 0
	v_add_f32_e32 v0, 1.0, v0
	v_rcp_f32_e32 v2, v0
	s_nop 0
	v_mul_f32_e32 v0, v21, v2
	v_mul_f32_e32 v0, v5, v0
	v_cvt_pk_bf16_f32 v0, v0, s0
	ds_write_b16 v96, v0 offset:5904
	v_mul_f32_e32 v0, 0xbfb8aa3b, v22
	v_exp_f32_e32 v0, v0
	s_nop 0
	v_add_f32_e32 v0, 1.0, v0
	v_rcp_f32_e32 v2, v0
	s_nop 0
	v_mul_f32_e32 v0, v22, v2
	v_mul_f32_e32 v0, v6, v0
	v_cvt_pk_bf16_f32 v0, v0, s0
	ds_write_b16 v96, v0 offset:6048
	v_mul_f32_e32 v0, 0xbfb8aa3b, v23
	v_exp_f32_e32 v0, v0
	s_nop 0
	v_add_f32_e32 v0, 1.0, v0
	v_rcp_f32_e32 v2, v0
	s_nop 0
	v_mul_f32_e32 v0, v23, v2
	v_mul_f32_e32 v0, v7, v0
	v_cvt_pk_bf16_f32 v0, v0, s0
	ds_write_b16 v96, v0 offset:6192
	v_mul_f32_e32 v0, 0xbfb8aa3b, v24
	v_exp_f32_e32 v0, v0
	s_nop 0
	v_add_f32_e32 v0, 1.0, v0
	v_rcp_f32_e32 v2, v0
	s_nop 0
	v_mul_f32_e32 v0, v24, v2
	v_mul_f32_e32 v0, v8, v0
	v_cvt_pk_bf16_f32 v0, v0, s0
	ds_write_b16 v96, v0 offset:6912
	v_mul_f32_e32 v0, 0xbfb8aa3b, v25
	v_exp_f32_e32 v0, v0
	s_nop 0
	v_add_f32_e32 v0, 1.0, v0
	v_rcp_f32_e32 v2, v0
	s_nop 0
	v_mul_f32_e32 v0, v25, v2
	v_mul_f32_e32 v0, v9, v0
	v_cvt_pk_bf16_f32 v0, v0, s0
	ds_write_b16 v96, v0 offset:7056
	v_mul_f32_e32 v0, 0xbfb8aa3b, v26
	v_exp_f32_e32 v0, v0
	s_nop 0
	v_add_f32_e32 v0, 1.0, v0
	v_rcp_f32_e32 v2, v0
	s_nop 0
	v_mul_f32_e32 v0, v26, v2
	v_mul_f32_e32 v0, v10, v0
	v_cvt_pk_bf16_f32 v0, v0, s0
	ds_write_b16 v96, v0 offset:7200
	v_mul_f32_e32 v0, 0xbfb8aa3b, v27
	v_exp_f32_e32 v0, v0
	s_nop 0
	v_add_f32_e32 v0, 1.0, v0
	v_rcp_f32_e32 v2, v0
	s_nop 0
	v_mul_f32_e32 v0, v27, v2
	v_mul_f32_e32 v0, v11, v0
	v_cvt_pk_bf16_f32 v0, v0, s0
	ds_write_b16 v96, v0 offset:7344
	v_mul_f32_e32 v0, 0xbfb8aa3b, v28
	v_exp_f32_e32 v0, v0
	s_nop 0
	v_add_f32_e32 v0, 1.0, v0
	v_rcp_f32_e32 v2, v0
	s_nop 0
	v_mul_f32_e32 v0, v28, v2
	v_mul_f32_e32 v0, v12, v0
	v_cvt_pk_bf16_f32 v0, v0, s0
	ds_write_b16 v96, v0 offset:8064
	v_mul_f32_e32 v0, 0xbfb8aa3b, v29
	v_exp_f32_e32 v0, v0
	s_nop 0
	v_add_f32_e32 v0, 1.0, v0
	v_rcp_f32_e32 v2, v0
	s_nop 0
	v_mul_f32_e32 v0, v29, v2
	v_mul_f32_e32 v0, v13, v0
	v_cvt_pk_bf16_f32 v0, v0, s0
	ds_write_b16 v96, v0 offset:8208
	v_mul_f32_e32 v0, 0xbfb8aa3b, v30
	v_exp_f32_e32 v0, v0
	s_nop 0
	v_add_f32_e32 v0, 1.0, v0
	v_rcp_f32_e32 v2, v0
	s_nop 0
	v_mul_f32_e32 v0, v30, v2
	v_mul_f32_e32 v0, v14, v0
	v_cvt_pk_bf16_f32 v0, v0, s0
	ds_write_b16 v96, v0 offset:8352
	v_mul_f32_e32 v0, 0xbfb8aa3b, v31
	v_exp_f32_e32 v0, v0
	s_nop 0
	v_add_f32_e32 v0, 1.0, v0
	v_rcp_f32_e32 v2, v0
	s_nop 0
	v_mul_f32_e32 v0, v31, v2
	v_mul_f32_e32 v0, v15, v0
	v_cvt_pk_bf16_f32 v0, v0, s0
	ds_write_b16 v96, v0 offset:8496
	v_or_b32_e32 v4, 2, v68
	s_waitcnt lgkmcnt(0)
	v_ashrrev_i32_e32 v5, 31, v4
	ds_read_b128 v[0:3], v128
	v_mad_i64_i32 v[6:7], s[0:1], v71, s23, v[4:5]
	v_lshlrev_b64 v[6:7], 10, v[6:7]
	v_lshl_add_u64 v[6:7], s[66:67], 0, v[6:7]
	v_lshl_add_u64 v[6:7], v[6:7], 0, v[176:177]
	v_lshl_add_u64 v[8:9], v[6:7], 0, v[66:67]
	s_waitcnt lgkmcnt(0)
	global_store_dwordx4 v[8:9], v[0:3], off
	ds_read_b128 v[0:3], v128 offset:2304
	v_lshl_add_u64 v[6:7], v[6:7], 0, v[64:65]
	v_mad_i64_i32 v[4:5], s[0:1], v70, s23, v[4:5]
	v_lshlrev_b64 v[4:5], 10, v[4:5]
	s_waitcnt lgkmcnt(0)
	global_store_dwordx4 v[6:7], v[0:3], off
	ds_read_b128 v[0:3], v128 offset:4608
	v_lshl_add_u64 v[4:5], s[66:67], 0, v[4:5]
	v_lshl_add_u64 v[4:5], v[4:5], 0, v[176:177]
	v_lshl_add_u64 v[6:7], v[4:5], 0, v[66:67]
	v_lshl_add_u64 v[4:5], v[4:5], 0, v[64:65]
	s_waitcnt lgkmcnt(0)
	global_store_dwordx4 v[6:7], v[0:3], off
	ds_read_b128 v[0:3], v128 offset:6912
	v_readlane_b32 s0, v254, 11
	s_add_i32 s2, s2, s0
	s_cmp_lt_i32 s2, s3
	s_waitcnt lgkmcnt(0)
	global_store_dwordx4 v[4:5], v[0:3], off
	s_waitcnt lgkmcnt(0)
	s_barrier
	s_cbranch_scc1 .LBB0_1031
